# SwiGLU epilogue P1/P8: exp-argument multiplies and 1+e adds as packed-f32 ops (64 fewer VALU per epilogue), stacked on v66
# speedup vs baseline: 1.0075x; 1.0075x over previous
.LBB0_208:
	s_add_u32 s4, s46, 0xfffffe00
	s_addc_u32 s5, s47, -1
	s_add_i32 s2, s76, s3
	v_lshl_add_u32 v140, v141, 4, s2
	ds_read_b128 v[152:155], v140
	ds_read_b128 v[156:159], v140 offset:256
	ds_read_b128 v[160:163], v140 offset:512
	ds_read_b128 v[164:167], v140 offset:768
	s_waitcnt lgkmcnt(0)
	s_waitcnt lgkmcnt(0)
	v_mov_b32_e32 v168, v153
	v_mov_b32_e32 v169, v154
	v_mov_b32_e32 v153, v155
	v_pk_add_f32 v[152:153], v[168:169], v[152:153]
	s_lshl_b32 s2, s10, 8
	v_add_f32_e32 v149, v152, v153
	v_mov_b32_e32 v152, v157
	v_mov_b32_e32 v153, v158
	v_mov_b32_e32 v157, v159
	v_fmamk_f32 v149, v149, 0x3a800000, v148
	v_pk_add_f32 v[152:153], v[152:153], v[156:157]
	v_rsq_f32_e32 v170, v149
	v_add_f32_e32 v149, v152, v153
	v_mov_b32_e32 v152, v161
	v_mov_b32_e32 v153, v162
	v_mov_b32_e32 v161, v163
	v_fmamk_f32 v149, v149, 0x3a800000, v148
	v_pk_add_f32 v[152:153], v[152:153], v[160:161]
	v_rsq_f32_e32 v171, v149
	v_add_f32_e32 v149, v152, v153
	v_mov_b32_e32 v152, v165
	v_mov_b32_e32 v153, v166
	v_mov_b32_e32 v165, v167
	v_fmamk_f32 v149, v149, 0x3a800000, v148
	v_pk_add_f32 v[152:153], v[152:153], v[164:165]
	v_rsq_f32_e32 v172, v149
	v_add_f32_e32 v149, v152, v153
	ds_read_b128 v[152:155], v140 offset:2048
	ds_read_b128 v[156:159], v140 offset:2304
	ds_read_b128 v[160:163], v140 offset:2560
	ds_read_b128 v[164:167], v140 offset:2816
	v_fmamk_f32 v149, v149, 0x3a800000, v148
	s_waitcnt lgkmcnt(0)
	v_mov_b32_e32 v168, v153
	v_mov_b32_e32 v169, v154
	v_mov_b32_e32 v153, v155
	v_pk_add_f32 v[152:153], v[168:169], v[152:153]
	v_rsq_f32_e32 v173, v149
	v_add_f32_e32 v140, v152, v153
	v_mov_b32_e32 v152, v157
	v_mov_b32_e32 v153, v158
	v_mov_b32_e32 v157, v159
	v_fmamk_f32 v140, v140, 0x3a800000, v148
	v_pk_add_f32 v[152:153], v[152:153], v[156:157]
	v_rsq_f32_e32 v168, v140
	v_add_f32_e32 v140, v152, v153
	v_mov_b32_e32 v152, v161
	v_mov_b32_e32 v153, v162
	v_mov_b32_e32 v161, v163
	v_fmamk_f32 v140, v140, 0x3a800000, v148
	v_pk_add_f32 v[152:153], v[152:153], v[160:161]
	v_rsq_f32_e32 v169, v140
	v_add_f32_e32 v140, v152, v153
	v_mov_b32_e32 v152, v165
	v_mov_b32_e32 v153, v166
	v_mov_b32_e32 v165, v167
	v_fmamk_f32 v140, v140, 0x3a800000, v148
	v_pk_add_f32 v[152:153], v[152:153], v[164:165]
	v_rsq_f32_e32 v149, v140
	v_add_f32_e32 v140, v152, v153
	s_add_i32 s2, s2, s59
	v_mul_f32_e32 v153, 0xbfb8aa3b, v170
	v_pk_mul_f32 v[154:155], v[118:119], v[152:153] op_sel:[0,1]
	v_pk_mul_f32 v[156:157], v[114:115], v[152:153] op_sel:[0,1]
	v_pk_mul_f32 v[158:159], v[120:121], v[152:153] op_sel:[0,1]
	v_pk_mul_f32 v[160:161], v[116:117], v[152:153] op_sel:[0,1]
	v_exp_f32_e32 v154, v154
	v_exp_f32_e32 v155, v155
	v_exp_f32_e32 v156, v156
	v_exp_f32_e32 v157, v157
	v_exp_f32_e32 v158, v158
	v_exp_f32_e32 v159, v159
	v_exp_f32_e32 v160, v160
	v_exp_f32_e32 v161, v161
	v_pk_add_f32 v[154:155], v[154:155], 1.0 op_sel_hi:[1,0]
	v_pk_add_f32 v[156:157], v[156:157], 1.0 op_sel_hi:[1,0]
	v_pk_add_f32 v[158:159], v[158:159], 1.0 op_sel_hi:[1,0]
	v_pk_add_f32 v[160:161], v[160:161], 1.0 op_sel_hi:[1,0]
	v_rcp_f32_e32 v154, v154
	v_rcp_f32_e32 v155, v155
	v_rcp_f32_e32 v156, v156
	v_rcp_f32_e32 v157, v157
	v_rcp_f32_e32 v158, v158
	v_rcp_f32_e32 v159, v159
	v_rcp_f32_e32 v160, v160
	v_rcp_f32_e32 v161, v161
	s_nop 0
	v_add_u32_e32 v141, s2, v141
	s_lshl_b32 s2, s60, 7
	s_or_b32 s2, s2, s61
	v_mul_f32_e32 v152, v170, v170
	v_lshl_add_u32 v150, v150, 3, s2
	v_pk_mul_f32 v[120:121], v[120:121], v[128:129]
	v_pk_mul_f32 v[118:119], v[118:119], v[126:127]
	v_pk_mul_f32 v[126:127], v[152:153], v[154:155] op_sel_hi:[0,1]
	v_pk_mul_f32 v[128:129], v[152:153], v[158:159] op_sel_hi:[0,1]
	v_pk_mul_f32 v[114:115], v[114:115], v[122:123]
	v_pk_mul_f32 v[122:123], v[152:153], v[156:157] op_sel_hi:[0,1]
	v_readlane_b32 s2, v255, 0
	v_pk_mul_f32 v[120:121], v[120:121], v[128:129]
	v_pk_mul_f32 v[118:119], v[118:119], v[126:127]
	v_pk_mul_f32 v[116:117], v[116:117], v[124:125]
	v_pk_mul_f32 v[124:125], v[152:153], v[160:161] op_sel_hi:[0,1]
	v_pk_mul_f32 v[114:115], v[114:115], v[122:123]
	v_readlane_b32 s3, v255, 1
	s_waitcnt lgkmcnt(0)
	v_ashrrev_i32_e32 v151, 31, v150
	v_pk_mul_f32 v[116:117], v[116:117], v[124:125]
	v_cvt_pk_bf16_f32 v118, v118, v119
	v_cvt_pk_bf16_f32 v119, v120, v121
	v_cvt_pk_bf16_f32 v120, v114, v115
	v_mov_b64_e32 v[114:115], s[2:3]
	v_cvt_pk_bf16_f32 v121, v116, v117
	v_mad_i64_i32 v[122:123], s[2:3], v141, s50, v[114:115]
	v_lshlrev_b64 v[116:117], 1, v[150:151]
	v_lshl_add_u64 v[122:123], v[122:123], 0, v[116:117]
	s_cmp_eq_u32 s98, 1
	s_cbranch_scc1 .Lwt_0
	global_store_dwordx4 v[122:123], v[118:121], off
	s_branch .Lwtd_0

.Lwtd_0:
	v_fmamk_f32 v140, v140, 0x3a800000, v148
	v_rsq_f32_e32 v140, v140
	v_mul_f32_e32 v120, 0xbfb8aa3b, v171
	v_pk_mul_f32 v[122:123], v[98:99], v[120:121] op_sel_hi:[1,0]
	v_pk_mul_f32 v[124:125], v[104:105], v[120:121] op_sel_hi:[1,0]
	v_pk_mul_f32 v[126:127], v[100:101], v[120:121] op_sel_hi:[1,0]
	v_pk_mul_f32 v[120:121], v[102:103], v[120:121] op_sel_hi:[1,0]
	v_exp_f32_e32 v122, v122
	v_exp_f32_e32 v123, v123
	v_exp_f32_e32 v124, v124
	v_exp_f32_e32 v125, v125
	v_exp_f32_e32 v126, v126
	v_exp_f32_e32 v127, v127
	v_exp_f32_e32 v120, v120
	v_exp_f32_e32 v121, v121
	v_pk_add_f32 v[122:123], v[122:123], 1.0 op_sel_hi:[1,0]
	v_pk_add_f32 v[124:125], v[124:125], 1.0 op_sel_hi:[1,0]
	v_pk_add_f32 v[126:127], v[126:127], 1.0 op_sel_hi:[1,0]
	v_pk_add_f32 v[120:121], v[120:121], 1.0 op_sel_hi:[1,0]
	v_rcp_f32_e32 v122, v122
	v_rcp_f32_e32 v123, v123
	v_rcp_f32_e32 v124, v124
	v_rcp_f32_e32 v125, v125
	v_rcp_f32_e32 v126, v126
	v_rcp_f32_e32 v127, v127
	v_rcp_f32_e32 v120, v120
	v_rcp_f32_e32 v121, v121
	s_nop 0
	v_add_u32_e32 v119, 16, v141
	v_mul_f32_e32 v118, v171, v171
	v_pk_mul_f32 v[102:103], v[102:103], v[110:111]
	v_pk_mul_f32 v[110:111], v[118:119], v[120:121] op_sel_hi:[0,1]
	v_pk_mul_f32 v[102:103], v[102:103], v[110:111]
	v_pk_mul_f32 v[100:101], v[100:101], v[108:109]
	v_pk_mul_f32 v[98:99], v[98:99], v[106:107]
	v_pk_mul_f32 v[106:107], v[118:119], v[122:123] op_sel_hi:[0,1]
	v_pk_mul_f32 v[108:109], v[118:119], v[126:127] op_sel_hi:[0,1]
	v_pk_mul_f32 v[104:105], v[104:105], v[112:113]
	v_pk_mul_f32 v[112:113], v[118:119], v[124:125] op_sel_hi:[0,1]
	v_pk_mul_f32 v[108:109], v[100:101], v[108:109]
	v_pk_mul_f32 v[100:101], v[98:99], v[106:107]
	v_cvt_pk_bf16_f32 v98, v102, v103
	v_mad_i64_i32 v[102:103], s[2:3], v119, s50, v[114:115]
	v_pk_mul_f32 v[104:105], v[104:105], v[112:113]
	v_lshl_add_u64 v[102:103], v[102:103], 0, v[116:117]
	v_cvt_pk_bf16_f32 v99, v104, v105
	v_cvt_pk_bf16_f32 v100, v100, v101
	v_cvt_pk_bf16_f32 v101, v108, v109
	s_cmp_eq_u32 s98, 1
	s_cbranch_scc1 .Lwt_1
	global_store_dwordx4 v[102:103], v[98:101], off
	s_branch .Lwtd_1

.Lwtd_1:
	s_andn2_b64 vcc, exec, s[0:1]
	s_nop 0
	v_mul_f32_e32 v100, 0xbfb8aa3b, v172
	v_pk_mul_f32 v[102:103], v[82:83], v[100:101] op_sel_hi:[1,0]
	v_pk_mul_f32 v[104:105], v[88:89], v[100:101] op_sel_hi:[1,0]
	v_pk_mul_f32 v[106:107], v[84:85], v[100:101] op_sel_hi:[1,0]
	v_pk_mul_f32 v[100:101], v[86:87], v[100:101] op_sel_hi:[1,0]
	v_exp_f32_e32 v102, v102
	v_exp_f32_e32 v103, v103
	v_exp_f32_e32 v104, v104
	v_exp_f32_e32 v105, v105
	v_exp_f32_e32 v106, v106
	v_exp_f32_e32 v107, v107
	v_exp_f32_e32 v100, v100
	v_exp_f32_e32 v101, v101
	v_pk_add_f32 v[102:103], v[102:103], 1.0 op_sel_hi:[1,0]
	v_pk_add_f32 v[104:105], v[104:105], 1.0 op_sel_hi:[1,0]
	v_pk_add_f32 v[106:107], v[106:107], 1.0 op_sel_hi:[1,0]
	v_pk_add_f32 v[100:101], v[100:101], 1.0 op_sel_hi:[1,0]
	v_rcp_f32_e32 v102, v102
	v_rcp_f32_e32 v103, v103
	v_rcp_f32_e32 v104, v104
	v_rcp_f32_e32 v105, v105
	v_rcp_f32_e32 v106, v106
	v_rcp_f32_e32 v107, v107
	v_rcp_f32_e32 v100, v100
	v_rcp_f32_e32 v101, v101
	s_nop 0
	v_add_u32_e32 v99, 32, v141
	v_mul_f32_e32 v98, v172, v172
	v_pk_mul_f32 v[86:87], v[86:87], v[94:95]
	v_pk_mul_f32 v[94:95], v[98:99], v[100:101] op_sel_hi:[0,1]
	v_pk_mul_f32 v[86:87], v[86:87], v[94:95]
	v_pk_mul_f32 v[84:85], v[84:85], v[92:93]
	v_pk_mul_f32 v[82:83], v[82:83], v[90:91]
	v_pk_mul_f32 v[90:91], v[98:99], v[102:103] op_sel_hi:[0,1]
	v_pk_mul_f32 v[92:93], v[98:99], v[106:107] op_sel_hi:[0,1]
	v_pk_mul_f32 v[88:89], v[88:89], v[96:97]
	v_pk_mul_f32 v[96:97], v[98:99], v[104:105] op_sel_hi:[0,1]
	v_pk_mul_f32 v[92:93], v[84:85], v[92:93]
	v_pk_mul_f32 v[84:85], v[82:83], v[90:91]
	v_cvt_pk_bf16_f32 v82, v86, v87
	v_mad_i64_i32 v[86:87], s[2:3], v99, s50, v[114:115]
	v_pk_mul_f32 v[88:89], v[88:89], v[96:97]
	v_lshl_add_u64 v[86:87], v[86:87], 0, v[116:117]
	v_cvt_pk_bf16_f32 v83, v88, v89
	v_cvt_pk_bf16_f32 v84, v84, v85
	v_cvt_pk_bf16_f32 v85, v92, v93
	s_cmp_eq_u32 s98, 1
	s_cbranch_scc1 .Lwt_2
	global_store_dwordx4 v[86:87], v[82:85], off
	s_branch .Lwtd_2

.Lwtd_2:
	s_nop 1
	v_mul_f32_e32 v84, 0xbfb8aa3b, v173
	v_pk_mul_f32 v[86:87], v[62:63], v[84:85] op_sel_hi:[1,0]
	v_pk_mul_f32 v[88:89], v[72:73], v[84:85] op_sel_hi:[1,0]
	v_pk_mul_f32 v[90:91], v[64:65], v[84:85] op_sel_hi:[1,0]
	v_pk_mul_f32 v[84:85], v[70:71], v[84:85] op_sel_hi:[1,0]
	v_exp_f32_e32 v86, v86
	v_exp_f32_e32 v87, v87
	v_exp_f32_e32 v88, v88
	v_exp_f32_e32 v89, v89
	v_exp_f32_e32 v90, v90
	v_exp_f32_e32 v91, v91
	v_exp_f32_e32 v84, v84
	v_exp_f32_e32 v85, v85
	v_pk_add_f32 v[86:87], v[86:87], 1.0 op_sel_hi:[1,0]
	v_pk_add_f32 v[88:89], v[88:89], 1.0 op_sel_hi:[1,0]
	v_pk_add_f32 v[90:91], v[90:91], 1.0 op_sel_hi:[1,0]
	v_pk_add_f32 v[84:85], v[84:85], 1.0 op_sel_hi:[1,0]
	v_rcp_f32_e32 v86, v86
	v_rcp_f32_e32 v87, v87
	v_rcp_f32_e32 v88, v88
	v_rcp_f32_e32 v89, v89
	v_rcp_f32_e32 v90, v90
	v_rcp_f32_e32 v91, v91
	v_rcp_f32_e32 v84, v84
	v_rcp_f32_e32 v85, v85
	s_nop 0
	v_add_u32_e32 v83, 48, v141
	v_mul_f32_e32 v82, v173, v173
	v_pk_mul_f32 v[70:71], v[70:71], v[78:79]
	v_pk_mul_f32 v[78:79], v[82:83], v[84:85] op_sel_hi:[0,1]
	v_pk_mul_f32 v[70:71], v[70:71], v[78:79]
	v_pk_mul_f32 v[64:65], v[64:65], v[76:77]
	v_pk_mul_f32 v[62:63], v[62:63], v[74:75]
	v_pk_mul_f32 v[74:75], v[82:83], v[86:87] op_sel_hi:[0,1]
	v_pk_mul_f32 v[76:77], v[82:83], v[90:91] op_sel_hi:[0,1]
	v_pk_mul_f32 v[72:73], v[72:73], v[80:81]
	v_pk_mul_f32 v[80:81], v[82:83], v[88:89] op_sel_hi:[0,1]
	v_pk_mul_f32 v[76:77], v[64:65], v[76:77]
	v_pk_mul_f32 v[64:65], v[62:63], v[74:75]
	v_cvt_pk_bf16_f32 v62, v70, v71
	v_mad_i64_i32 v[70:71], s[2:3], v83, s50, v[114:115]
	v_pk_mul_f32 v[72:73], v[72:73], v[80:81]
	v_lshl_add_u64 v[70:71], v[70:71], 0, v[116:117]
	v_cvt_pk_bf16_f32 v63, v72, v73
	v_cvt_pk_bf16_f32 v64, v64, v65
	v_cvt_pk_bf16_f32 v65, v76, v77
	s_cmp_eq_u32 s98, 1
	s_cbranch_scc1 .Lwt_3
	global_store_dwordx4 v[70:71], v[62:65], off
	s_branch .Lwtd_3

.Lwtd_3:
	s_nop 1
	v_mul_f32_e32 v64, 0xbfb8aa3b, v168
	v_pk_mul_f32 v[70:71], v[50:51], v[64:65] op_sel_hi:[1,0]
	v_pk_mul_f32 v[72:73], v[56:57], v[64:65] op_sel_hi:[1,0]
	v_pk_mul_f32 v[74:75], v[52:53], v[64:65] op_sel_hi:[1,0]
	v_pk_mul_f32 v[64:65], v[54:55], v[64:65] op_sel_hi:[1,0]
	v_exp_f32_e32 v70, v70
	v_exp_f32_e32 v71, v71
	v_exp_f32_e32 v72, v72
	v_exp_f32_e32 v73, v73
	v_exp_f32_e32 v74, v74
	v_exp_f32_e32 v75, v75
	v_exp_f32_e32 v64, v64
	v_exp_f32_e32 v65, v65
	v_pk_add_f32 v[70:71], v[70:71], 1.0 op_sel_hi:[1,0]
	v_pk_add_f32 v[72:73], v[72:73], 1.0 op_sel_hi:[1,0]
	v_pk_add_f32 v[74:75], v[74:75], 1.0 op_sel_hi:[1,0]
	v_pk_add_f32 v[64:65], v[64:65], 1.0 op_sel_hi:[1,0]
	v_rcp_f32_e32 v70, v70
	v_rcp_f32_e32 v71, v71
	v_rcp_f32_e32 v72, v72
	v_rcp_f32_e32 v73, v73
	v_rcp_f32_e32 v74, v74
	v_rcp_f32_e32 v75, v75
	v_rcp_f32_e32 v64, v64
	v_rcp_f32_e32 v65, v65
	s_nop 0
	v_add_u32_e32 v63, 0x80, v141
	v_mul_f32_e32 v62, v168, v168
	v_pk_mul_f32 v[54:55], v[54:55], v[66:67]
	v_pk_mul_f32 v[64:65], v[62:63], v[64:65] op_sel_hi:[0,1]
	v_pk_mul_f32 v[54:55], v[54:55], v[64:65]
	v_pk_mul_f32 v[52:53], v[52:53], v[60:61]
	v_pk_mul_f32 v[50:51], v[50:51], v[58:59]
	v_pk_mul_f32 v[58:59], v[62:63], v[70:71] op_sel_hi:[0,1]
	v_pk_mul_f32 v[60:61], v[62:63], v[74:75] op_sel_hi:[0,1]
	v_pk_mul_f32 v[56:57], v[56:57], v[68:69]
	v_pk_mul_f32 v[66:67], v[62:63], v[72:73] op_sel_hi:[0,1]
	v_pk_mul_f32 v[60:61], v[52:53], v[60:61]
	v_pk_mul_f32 v[52:53], v[50:51], v[58:59]
	v_cvt_pk_bf16_f32 v50, v54, v55
	v_mad_i64_i32 v[54:55], s[2:3], v63, s50, v[114:115]
	v_pk_mul_f32 v[56:57], v[56:57], v[66:67]
	v_lshl_add_u64 v[54:55], v[54:55], 0, v[116:117]
	v_cvt_pk_bf16_f32 v51, v56, v57
	v_cvt_pk_bf16_f32 v52, v52, v53
	v_cvt_pk_bf16_f32 v53, v60, v61
	s_cmp_eq_u32 s98, 1
	s_cbranch_scc1 .Lwt_4
	global_store_dwordx4 v[54:55], v[50:53], off
	s_branch .Lwtd_4

.Lwtd_4:
	s_nop 1
	v_mul_f32_e32 v52, 0xbfb8aa3b, v169
	v_pk_mul_f32 v[54:55], v[34:35], v[52:53] op_sel_hi:[1,0]
	v_pk_mul_f32 v[56:57], v[40:41], v[52:53] op_sel_hi:[1,0]
	v_pk_mul_f32 v[58:59], v[36:37], v[52:53] op_sel_hi:[1,0]
	v_pk_mul_f32 v[52:53], v[38:39], v[52:53] op_sel_hi:[1,0]
	v_exp_f32_e32 v54, v54
	v_exp_f32_e32 v55, v55
	v_exp_f32_e32 v56, v56
	v_exp_f32_e32 v57, v57
	v_exp_f32_e32 v58, v58
	v_exp_f32_e32 v59, v59
	v_exp_f32_e32 v52, v52
	v_exp_f32_e32 v53, v53
	v_pk_add_f32 v[54:55], v[54:55], 1.0 op_sel_hi:[1,0]
	v_pk_add_f32 v[56:57], v[56:57], 1.0 op_sel_hi:[1,0]
	v_pk_add_f32 v[58:59], v[58:59], 1.0 op_sel_hi:[1,0]
	v_pk_add_f32 v[52:53], v[52:53], 1.0 op_sel_hi:[1,0]
	v_rcp_f32_e32 v54, v54
	v_rcp_f32_e32 v55, v55
	v_rcp_f32_e32 v56, v56
	v_rcp_f32_e32 v57, v57
	v_rcp_f32_e32 v58, v58
	v_rcp_f32_e32 v59, v59
	v_rcp_f32_e32 v52, v52
	v_rcp_f32_e32 v53, v53
	s_nop 0
	v_add_u32_e32 v51, 0x90, v141
	v_mul_f32_e32 v50, v169, v169
	v_pk_mul_f32 v[38:39], v[38:39], v[46:47]
	v_pk_mul_f32 v[46:47], v[50:51], v[52:53] op_sel_hi:[0,1]
	v_pk_mul_f32 v[38:39], v[38:39], v[46:47]
	v_pk_mul_f32 v[36:37], v[36:37], v[44:45]
	v_pk_mul_f32 v[34:35], v[34:35], v[42:43]
	v_pk_mul_f32 v[42:43], v[50:51], v[54:55] op_sel_hi:[0,1]
	v_pk_mul_f32 v[44:45], v[50:51], v[58:59] op_sel_hi:[0,1]
	v_pk_mul_f32 v[40:41], v[40:41], v[48:49]
	v_pk_mul_f32 v[48:49], v[50:51], v[56:57] op_sel_hi:[0,1]
	v_pk_mul_f32 v[44:45], v[36:37], v[44:45]
	v_pk_mul_f32 v[36:37], v[34:35], v[42:43]
	v_cvt_pk_bf16_f32 v34, v38, v39
	v_mad_i64_i32 v[38:39], s[2:3], v51, s50, v[114:115]
	v_pk_mul_f32 v[40:41], v[40:41], v[48:49]
	v_lshl_add_u64 v[38:39], v[38:39], 0, v[116:117]
	v_cvt_pk_bf16_f32 v35, v40, v41
	v_cvt_pk_bf16_f32 v36, v36, v37
	v_cvt_pk_bf16_f32 v37, v44, v45
	s_cmp_eq_u32 s98, 1
	s_cbranch_scc1 .Lwt_5
	global_store_dwordx4 v[38:39], v[34:37], off
	s_branch .Lwtd_5

.Lwtd_5:
	s_nop 1
	v_mul_f32_e32 v36, 0xbfb8aa3b, v149
	v_pk_mul_f32 v[38:39], v[18:19], v[36:37] op_sel_hi:[1,0]
	v_pk_mul_f32 v[40:41], v[24:25], v[36:37] op_sel_hi:[1,0]
	v_pk_mul_f32 v[42:43], v[20:21], v[36:37] op_sel_hi:[1,0]
	v_pk_mul_f32 v[36:37], v[22:23], v[36:37] op_sel_hi:[1,0]
	v_exp_f32_e32 v38, v38
	v_exp_f32_e32 v39, v39
	v_exp_f32_e32 v40, v40
	v_exp_f32_e32 v41, v41
	v_exp_f32_e32 v42, v42
	v_exp_f32_e32 v43, v43
	v_exp_f32_e32 v36, v36
	v_exp_f32_e32 v37, v37
	v_pk_add_f32 v[38:39], v[38:39], 1.0 op_sel_hi:[1,0]
	v_pk_add_f32 v[40:41], v[40:41], 1.0 op_sel_hi:[1,0]
	v_pk_add_f32 v[42:43], v[42:43], 1.0 op_sel_hi:[1,0]
	v_pk_add_f32 v[36:37], v[36:37], 1.0 op_sel_hi:[1,0]
	v_rcp_f32_e32 v38, v38
	v_rcp_f32_e32 v39, v39
	v_rcp_f32_e32 v40, v40
	v_rcp_f32_e32 v41, v41
	v_rcp_f32_e32 v42, v42
	v_rcp_f32_e32 v43, v43
	v_rcp_f32_e32 v36, v36
	v_rcp_f32_e32 v37, v37
	s_nop 0
	v_add_u32_e32 v35, 0xa0, v141
	v_mul_f32_e32 v34, v149, v149
	v_pk_mul_f32 v[22:23], v[22:23], v[30:31]
	v_pk_mul_f32 v[30:31], v[34:35], v[36:37] op_sel_hi:[0,1]
	v_pk_mul_f32 v[22:23], v[22:23], v[30:31]
	v_pk_mul_f32 v[20:21], v[20:21], v[28:29]
	v_pk_mul_f32 v[18:19], v[18:19], v[26:27]
	v_pk_mul_f32 v[26:27], v[34:35], v[38:39] op_sel_hi:[0,1]
	v_pk_mul_f32 v[28:29], v[34:35], v[42:43] op_sel_hi:[0,1]
	v_pk_mul_f32 v[24:25], v[24:25], v[32:33]
	v_pk_mul_f32 v[32:33], v[34:35], v[40:41] op_sel_hi:[0,1]
	v_pk_mul_f32 v[28:29], v[20:21], v[28:29]
	v_pk_mul_f32 v[20:21], v[18:19], v[26:27]
	v_cvt_pk_bf16_f32 v18, v22, v23
	v_mad_i64_i32 v[22:23], s[2:3], v35, s50, v[114:115]
	v_pk_mul_f32 v[24:25], v[24:25], v[32:33]
	v_lshl_add_u64 v[22:23], v[22:23], 0, v[116:117]
	v_cvt_pk_bf16_f32 v19, v24, v25
	v_cvt_pk_bf16_f32 v20, v20, v21
	v_cvt_pk_bf16_f32 v21, v28, v29
	s_cmp_eq_u32 s98, 1
	s_cbranch_scc1 .Lwt_6
	global_store_dwordx4 v[22:23], v[18:21], off
	s_branch .Lwtd_6

.Lwtd_6:
	s_nop 1
	v_add_u32_e32 v19, 0xb0, v141
	v_mul_f32_e32 v18, v140, v140
	v_mul_f32_e32 v20, 0xbfb8aa3b, v140
	v_pk_mul_f32 v[22:23], v[2:3], v[20:21] op_sel_hi:[1,0]
	v_pk_mul_f32 v[24:25], v[8:9], v[20:21] op_sel_hi:[1,0]
	v_pk_mul_f32 v[26:27], v[4:5], v[20:21] op_sel_hi:[1,0]
	v_pk_mul_f32 v[20:21], v[6:7], v[20:21] op_sel_hi:[1,0]
	v_exp_f32_e32 v22, v22
	v_exp_f32_e32 v23, v23
	v_exp_f32_e32 v24, v24
	v_exp_f32_e32 v25, v25
	v_exp_f32_e32 v26, v26
	v_exp_f32_e32 v27, v27
	v_exp_f32_e32 v20, v20
	v_exp_f32_e32 v21, v21
	v_pk_add_f32 v[22:23], v[22:23], 1.0 op_sel_hi:[1,0]
	v_pk_add_f32 v[24:25], v[24:25], 1.0 op_sel_hi:[1,0]
	v_pk_add_f32 v[26:27], v[26:27], 1.0 op_sel_hi:[1,0]
	v_pk_add_f32 v[20:21], v[20:21], 1.0 op_sel_hi:[1,0]
	v_rcp_f32_e32 v22, v22
	v_rcp_f32_e32 v23, v23
	v_rcp_f32_e32 v24, v24
	v_rcp_f32_e32 v25, v25
	v_rcp_f32_e32 v26, v26
	v_rcp_f32_e32 v27, v27
	v_rcp_f32_e32 v20, v20
	v_rcp_f32_e32 v21, v21
	s_nop 0
	v_pk_mul_f32 v[6:7], v[6:7], v[14:15]
	v_pk_mul_f32 v[14:15], v[18:19], v[20:21] op_sel_hi:[0,1]
	v_pk_mul_f32 v[6:7], v[6:7], v[14:15]
	v_pk_mul_f32 v[4:5], v[4:5], v[12:13]
	v_pk_mul_f32 v[2:3], v[2:3], v[10:11]
	v_pk_mul_f32 v[10:11], v[18:19], v[22:23] op_sel_hi:[0,1]
	v_pk_mul_f32 v[12:13], v[18:19], v[26:27] op_sel_hi:[0,1]
	v_pk_mul_f32 v[12:13], v[4:5], v[12:13]
	v_pk_mul_f32 v[4:5], v[2:3], v[10:11]
	v_cvt_pk_bf16_f32 v2, v6, v7
	v_mad_i64_i32 v[6:7], s[2:3], v19, s50, v[114:115]
	v_pk_mul_f32 v[8:9], v[8:9], v[16:17]
	v_pk_mul_f32 v[16:17], v[18:19], v[24:25] op_sel_hi:[0,1]
	v_lshl_add_u64 v[6:7], v[6:7], 0, v[116:117]
	v_pk_mul_f32 v[8:9], v[8:9], v[16:17]
	s_nop 0
	v_cvt_pk_bf16_f32 v3, v8, v9
	v_cvt_pk_bf16_f32 v4, v4, v5
	v_cvt_pk_bf16_f32 v5, v12, v13
	s_cmp_eq_u32 s98, 1
	s_cbranch_scc1 .Lwt_7
	global_store_dwordx4 v[6:7], v[2:5], off
	s_branch .Lwtd_7

.LBB0_1725:
	s_add_u32 s4, s50, 0xfffffe00
	s_addc_u32 s5, s51, -1
	s_add_i32 s3, s88, s12
	v_lshl_add_u32 v140, v141, 4, s3
	ds_read_b128 v[152:155], v140
	ds_read_b128 v[156:159], v140 offset:256
	ds_read_b128 v[160:163], v140 offset:512
	ds_read_b128 v[164:167], v140 offset:768
	s_waitcnt lgkmcnt(0)
	s_waitcnt lgkmcnt(0)
	v_mov_b32_e32 v168, v153
	v_mov_b32_e32 v169, v154
	v_mov_b32_e32 v153, v155
	v_pk_add_f32 v[152:153], v[168:169], v[152:153]
	s_lshl_b32 s3, s10, 8
	v_add_f32_e32 v149, v152, v153
	v_mov_b32_e32 v152, v157
	v_mov_b32_e32 v153, v158
	v_mov_b32_e32 v157, v159
	v_fmamk_f32 v149, v149, 0x3a800000, v148
	v_pk_add_f32 v[152:153], v[152:153], v[156:157]
	v_rsq_f32_e32 v170, v149
	v_add_f32_e32 v149, v152, v153
	v_mov_b32_e32 v152, v161
	v_mov_b32_e32 v153, v162
	v_mov_b32_e32 v161, v163
	v_fmamk_f32 v149, v149, 0x3a800000, v148
	v_pk_add_f32 v[152:153], v[152:153], v[160:161]
	v_rsq_f32_e32 v171, v149
	v_add_f32_e32 v149, v152, v153
	v_mov_b32_e32 v152, v165
	v_mov_b32_e32 v153, v166
	v_mov_b32_e32 v165, v167
	v_fmamk_f32 v149, v149, 0x3a800000, v148
	v_pk_add_f32 v[152:153], v[152:153], v[164:165]
	v_rsq_f32_e32 v172, v149
	v_add_f32_e32 v149, v152, v153
	ds_read_b128 v[152:155], v140 offset:2048
	ds_read_b128 v[156:159], v140 offset:2304
	ds_read_b128 v[160:163], v140 offset:2560
	ds_read_b128 v[164:167], v140 offset:2816
	v_fmamk_f32 v149, v149, 0x3a800000, v148
	s_waitcnt lgkmcnt(0)
	v_mov_b32_e32 v168, v153
	v_mov_b32_e32 v169, v154
	v_mov_b32_e32 v153, v155
	v_pk_add_f32 v[152:153], v[168:169], v[152:153]
	v_rsq_f32_e32 v173, v149
	v_add_f32_e32 v140, v152, v153
	v_mov_b32_e32 v152, v157
	v_mov_b32_e32 v153, v158
	v_mov_b32_e32 v157, v159
	v_fmamk_f32 v140, v140, 0x3a800000, v148
	v_pk_add_f32 v[152:153], v[152:153], v[156:157]
	v_rsq_f32_e32 v168, v140
	v_add_f32_e32 v140, v152, v153
	v_mov_b32_e32 v152, v161
	v_mov_b32_e32 v153, v162
	v_mov_b32_e32 v161, v163
	v_fmamk_f32 v140, v140, 0x3a800000, v148
	v_pk_add_f32 v[152:153], v[152:153], v[160:161]
	v_rsq_f32_e32 v169, v140
	v_add_f32_e32 v140, v152, v153
	v_mov_b32_e32 v152, v165
	v_mov_b32_e32 v153, v166
	v_mov_b32_e32 v165, v167
	v_fmamk_f32 v140, v140, 0x3a800000, v148
	v_pk_add_f32 v[152:153], v[152:153], v[164:165]
	v_rsq_f32_e32 v149, v140
	v_add_f32_e32 v140, v152, v153
	v_mul_f32_e32 v153, 0xbfb8aa3b, v170
	v_pk_mul_f32 v[154:155], v[118:119], v[152:153] op_sel:[0,1]
	v_pk_mul_f32 v[156:157], v[114:115], v[152:153] op_sel:[0,1]
	v_pk_mul_f32 v[158:159], v[120:121], v[152:153] op_sel:[0,1]
	v_pk_mul_f32 v[160:161], v[116:117], v[152:153] op_sel:[0,1]
	v_exp_f32_e32 v154, v154
	v_exp_f32_e32 v155, v155
	v_exp_f32_e32 v156, v156
	v_exp_f32_e32 v157, v157
	v_exp_f32_e32 v158, v158
	v_exp_f32_e32 v159, v159
	v_exp_f32_e32 v160, v160
	v_exp_f32_e32 v161, v161
	v_pk_add_f32 v[154:155], v[154:155], 1.0 op_sel_hi:[1,0]
	v_pk_add_f32 v[156:157], v[156:157], 1.0 op_sel_hi:[1,0]
	v_pk_add_f32 v[158:159], v[158:159], 1.0 op_sel_hi:[1,0]
	v_pk_add_f32 v[160:161], v[160:161], 1.0 op_sel_hi:[1,0]
	v_rcp_f32_e32 v154, v154
	v_rcp_f32_e32 v155, v155
	v_rcp_f32_e32 v156, v156
	v_rcp_f32_e32 v157, v157
	v_rcp_f32_e32 v158, v158
	v_rcp_f32_e32 v159, v159
	v_rcp_f32_e32 v160, v160
	v_rcp_f32_e32 v161, v161
	s_nop 0
	s_add_i32 s3, s3, s82
	v_add_u32_e32 v141, s3, v141
	s_lshl_b32 s3, s83, 7
	v_mul_f32_e32 v152, v170, v170
	s_or_b32 s3, s3, s84
	v_pk_mul_f32 v[120:121], v[120:121], v[128:129]
	v_pk_mul_f32 v[118:119], v[118:119], v[126:127]
	v_pk_mul_f32 v[126:127], v[152:153], v[154:155] op_sel_hi:[0,1]
	v_pk_mul_f32 v[128:129], v[152:153], v[158:159] op_sel_hi:[0,1]
	v_pk_mul_f32 v[114:115], v[114:115], v[122:123]
	v_pk_mul_f32 v[122:123], v[152:153], v[156:157] op_sel_hi:[0,1]
	v_readlane_b32 s12, v255, 0
	v_lshl_add_u32 v150, v150, 3, s3
	v_pk_mul_f32 v[120:121], v[120:121], v[128:129]
	v_pk_mul_f32 v[118:119], v[118:119], v[126:127]
	v_pk_mul_f32 v[116:117], v[116:117], v[124:125]
	v_pk_mul_f32 v[124:125], v[152:153], v[160:161] op_sel_hi:[0,1]
	v_pk_mul_f32 v[114:115], v[114:115], v[122:123]
	v_readlane_b32 s13, v255, 1
	s_waitcnt lgkmcnt(0)
	v_ashrrev_i32_e32 v151, 31, v150
	v_pk_mul_f32 v[116:117], v[116:117], v[124:125]
	v_cvt_pk_bf16_f32 v118, v118, v119
	v_cvt_pk_bf16_f32 v119, v120, v121
	v_cvt_pk_bf16_f32 v120, v114, v115
	v_mov_b64_e32 v[114:115], s[12:13]
	v_cvt_pk_bf16_f32 v121, v116, v117
	v_mad_i64_i32 v[122:123], s[12:13], v141, s91, v[114:115]
	v_lshlrev_b64 v[116:117], 1, v[150:151]
	v_lshl_add_u64 v[122:123], v[122:123], 0, v[116:117]
	s_cmp_eq_u32 s98, 1
	s_cbranch_scc1 .Lwt_8
	global_store_dwordx4 v[122:123], v[118:121], off
	s_branch .Lwtd_8

.Lwtd_8:
	v_fmamk_f32 v140, v140, 0x3a800000, v148
	v_rsq_f32_e32 v140, v140
	v_mul_f32_e32 v120, 0xbfb8aa3b, v171
	v_pk_mul_f32 v[122:123], v[98:99], v[120:121] op_sel_hi:[1,0]
	v_pk_mul_f32 v[124:125], v[104:105], v[120:121] op_sel_hi:[1,0]
	v_pk_mul_f32 v[126:127], v[100:101], v[120:121] op_sel_hi:[1,0]
	v_pk_mul_f32 v[120:121], v[102:103], v[120:121] op_sel_hi:[1,0]
	v_exp_f32_e32 v122, v122
	v_exp_f32_e32 v123, v123
	v_exp_f32_e32 v124, v124
	v_exp_f32_e32 v125, v125
	v_exp_f32_e32 v126, v126
	v_exp_f32_e32 v127, v127
	v_exp_f32_e32 v120, v120
	v_exp_f32_e32 v121, v121
	v_pk_add_f32 v[122:123], v[122:123], 1.0 op_sel_hi:[1,0]
	v_pk_add_f32 v[124:125], v[124:125], 1.0 op_sel_hi:[1,0]
	v_pk_add_f32 v[126:127], v[126:127], 1.0 op_sel_hi:[1,0]
	v_pk_add_f32 v[120:121], v[120:121], 1.0 op_sel_hi:[1,0]
	v_rcp_f32_e32 v122, v122
	v_rcp_f32_e32 v123, v123
	v_rcp_f32_e32 v124, v124
	v_rcp_f32_e32 v125, v125
	v_rcp_f32_e32 v126, v126
	v_rcp_f32_e32 v127, v127
	v_rcp_f32_e32 v120, v120
	v_rcp_f32_e32 v121, v121
	s_nop 0
	v_add_u32_e32 v119, 16, v141
	v_mul_f32_e32 v118, v171, v171
	v_pk_mul_f32 v[102:103], v[102:103], v[110:111]
	v_pk_mul_f32 v[110:111], v[118:119], v[120:121] op_sel_hi:[0,1]
	v_pk_mul_f32 v[102:103], v[102:103], v[110:111]
	v_pk_mul_f32 v[100:101], v[100:101], v[108:109]
	v_pk_mul_f32 v[98:99], v[98:99], v[106:107]
	v_pk_mul_f32 v[106:107], v[118:119], v[122:123] op_sel_hi:[0,1]
	v_pk_mul_f32 v[108:109], v[118:119], v[126:127] op_sel_hi:[0,1]
	v_pk_mul_f32 v[104:105], v[104:105], v[112:113]
	v_pk_mul_f32 v[112:113], v[118:119], v[124:125] op_sel_hi:[0,1]
	v_pk_mul_f32 v[108:109], v[100:101], v[108:109]
	v_pk_mul_f32 v[100:101], v[98:99], v[106:107]
	v_cvt_pk_bf16_f32 v98, v102, v103
	v_mad_i64_i32 v[102:103], s[12:13], v119, s91, v[114:115]
	v_pk_mul_f32 v[104:105], v[104:105], v[112:113]
	v_lshl_add_u64 v[102:103], v[102:103], 0, v[116:117]
	v_cvt_pk_bf16_f32 v99, v104, v105
	v_cvt_pk_bf16_f32 v100, v100, v101
	v_cvt_pk_bf16_f32 v101, v108, v109
	s_cmp_eq_u32 s98, 1
	s_cbranch_scc1 .Lwt_9
	global_store_dwordx4 v[102:103], v[98:101], off
	s_branch .Lwtd_9

.Lwtd_9:
	s_andn2_b64 vcc, exec, s[0:1]
	s_nop 0
	v_mul_f32_e32 v100, 0xbfb8aa3b, v172
	v_pk_mul_f32 v[102:103], v[82:83], v[100:101] op_sel_hi:[1,0]
	v_pk_mul_f32 v[104:105], v[88:89], v[100:101] op_sel_hi:[1,0]
	v_pk_mul_f32 v[106:107], v[84:85], v[100:101] op_sel_hi:[1,0]
	v_pk_mul_f32 v[100:101], v[86:87], v[100:101] op_sel_hi:[1,0]
	v_exp_f32_e32 v102, v102
	v_exp_f32_e32 v103, v103
	v_exp_f32_e32 v104, v104
	v_exp_f32_e32 v105, v105
	v_exp_f32_e32 v106, v106
	v_exp_f32_e32 v107, v107
	v_exp_f32_e32 v100, v100
	v_exp_f32_e32 v101, v101
	v_pk_add_f32 v[102:103], v[102:103], 1.0 op_sel_hi:[1,0]
	v_pk_add_f32 v[104:105], v[104:105], 1.0 op_sel_hi:[1,0]
	v_pk_add_f32 v[106:107], v[106:107], 1.0 op_sel_hi:[1,0]
	v_pk_add_f32 v[100:101], v[100:101], 1.0 op_sel_hi:[1,0]
	v_rcp_f32_e32 v102, v102
	v_rcp_f32_e32 v103, v103
	v_rcp_f32_e32 v104, v104
	v_rcp_f32_e32 v105, v105
	v_rcp_f32_e32 v106, v106
	v_rcp_f32_e32 v107, v107
	v_rcp_f32_e32 v100, v100
	v_rcp_f32_e32 v101, v101
	s_nop 0
	v_add_u32_e32 v99, 32, v141
	v_mul_f32_e32 v98, v172, v172
	v_pk_mul_f32 v[86:87], v[86:87], v[94:95]
	v_pk_mul_f32 v[94:95], v[98:99], v[100:101] op_sel_hi:[0,1]
	v_pk_mul_f32 v[86:87], v[86:87], v[94:95]
	v_pk_mul_f32 v[84:85], v[84:85], v[92:93]
	v_pk_mul_f32 v[82:83], v[82:83], v[90:91]
	v_pk_mul_f32 v[90:91], v[98:99], v[102:103] op_sel_hi:[0,1]
	v_pk_mul_f32 v[92:93], v[98:99], v[106:107] op_sel_hi:[0,1]
	v_pk_mul_f32 v[88:89], v[88:89], v[96:97]
	v_pk_mul_f32 v[96:97], v[98:99], v[104:105] op_sel_hi:[0,1]
	v_pk_mul_f32 v[92:93], v[84:85], v[92:93]
	v_pk_mul_f32 v[84:85], v[82:83], v[90:91]
	v_cvt_pk_bf16_f32 v82, v86, v87
	v_mad_i64_i32 v[86:87], s[12:13], v99, s91, v[114:115]
	v_pk_mul_f32 v[88:89], v[88:89], v[96:97]
	v_lshl_add_u64 v[86:87], v[86:87], 0, v[116:117]
	v_cvt_pk_bf16_f32 v83, v88, v89
	v_cvt_pk_bf16_f32 v84, v84, v85
	v_cvt_pk_bf16_f32 v85, v92, v93
	s_cmp_eq_u32 s98, 1
	s_cbranch_scc1 .Lwt_10
	global_store_dwordx4 v[86:87], v[82:85], off
	s_branch .Lwtd_10

.Lwtd_10:
	s_nop 1
	v_mul_f32_e32 v84, 0xbfb8aa3b, v173
	v_pk_mul_f32 v[86:87], v[62:63], v[84:85] op_sel_hi:[1,0]
	v_pk_mul_f32 v[88:89], v[72:73], v[84:85] op_sel_hi:[1,0]
	v_pk_mul_f32 v[90:91], v[64:65], v[84:85] op_sel_hi:[1,0]
	v_pk_mul_f32 v[84:85], v[70:71], v[84:85] op_sel_hi:[1,0]
	v_exp_f32_e32 v86, v86
	v_exp_f32_e32 v87, v87
	v_exp_f32_e32 v88, v88
	v_exp_f32_e32 v89, v89
	v_exp_f32_e32 v90, v90
	v_exp_f32_e32 v91, v91
	v_exp_f32_e32 v84, v84
	v_exp_f32_e32 v85, v85
	v_pk_add_f32 v[86:87], v[86:87], 1.0 op_sel_hi:[1,0]
	v_pk_add_f32 v[88:89], v[88:89], 1.0 op_sel_hi:[1,0]
	v_pk_add_f32 v[90:91], v[90:91], 1.0 op_sel_hi:[1,0]
	v_pk_add_f32 v[84:85], v[84:85], 1.0 op_sel_hi:[1,0]
	v_rcp_f32_e32 v86, v86
	v_rcp_f32_e32 v87, v87
	v_rcp_f32_e32 v88, v88
	v_rcp_f32_e32 v89, v89
	v_rcp_f32_e32 v90, v90
	v_rcp_f32_e32 v91, v91
	v_rcp_f32_e32 v84, v84
	v_rcp_f32_e32 v85, v85
	s_nop 0
	v_add_u32_e32 v83, 48, v141
	v_mul_f32_e32 v82, v173, v173
	v_pk_mul_f32 v[70:71], v[70:71], v[78:79]
	v_pk_mul_f32 v[78:79], v[82:83], v[84:85] op_sel_hi:[0,1]
	v_pk_mul_f32 v[70:71], v[70:71], v[78:79]
	v_pk_mul_f32 v[64:65], v[64:65], v[76:77]
	v_pk_mul_f32 v[62:63], v[62:63], v[74:75]
	v_pk_mul_f32 v[74:75], v[82:83], v[86:87] op_sel_hi:[0,1]
	v_pk_mul_f32 v[76:77], v[82:83], v[90:91] op_sel_hi:[0,1]
	v_pk_mul_f32 v[72:73], v[72:73], v[80:81]
	v_pk_mul_f32 v[80:81], v[82:83], v[88:89] op_sel_hi:[0,1]
	v_pk_mul_f32 v[76:77], v[64:65], v[76:77]
	v_pk_mul_f32 v[64:65], v[62:63], v[74:75]
	v_cvt_pk_bf16_f32 v62, v70, v71
	v_mad_i64_i32 v[70:71], s[12:13], v83, s91, v[114:115]
	v_pk_mul_f32 v[72:73], v[72:73], v[80:81]
	v_lshl_add_u64 v[70:71], v[70:71], 0, v[116:117]
	v_cvt_pk_bf16_f32 v63, v72, v73
	v_cvt_pk_bf16_f32 v64, v64, v65
	v_cvt_pk_bf16_f32 v65, v76, v77
	s_cmp_eq_u32 s98, 1
	s_cbranch_scc1 .Lwt_11
	global_store_dwordx4 v[70:71], v[62:65], off
	s_branch .Lwtd_11

.Lwtd_11:
	s_nop 1
	v_mul_f32_e32 v64, 0xbfb8aa3b, v168
	v_pk_mul_f32 v[70:71], v[50:51], v[64:65] op_sel_hi:[1,0]
	v_pk_mul_f32 v[72:73], v[56:57], v[64:65] op_sel_hi:[1,0]
	v_pk_mul_f32 v[74:75], v[52:53], v[64:65] op_sel_hi:[1,0]
	v_pk_mul_f32 v[64:65], v[54:55], v[64:65] op_sel_hi:[1,0]
	v_exp_f32_e32 v70, v70
	v_exp_f32_e32 v71, v71
	v_exp_f32_e32 v72, v72
	v_exp_f32_e32 v73, v73
	v_exp_f32_e32 v74, v74
	v_exp_f32_e32 v75, v75
	v_exp_f32_e32 v64, v64
	v_exp_f32_e32 v65, v65
	v_pk_add_f32 v[70:71], v[70:71], 1.0 op_sel_hi:[1,0]
	v_pk_add_f32 v[72:73], v[72:73], 1.0 op_sel_hi:[1,0]
	v_pk_add_f32 v[74:75], v[74:75], 1.0 op_sel_hi:[1,0]
	v_pk_add_f32 v[64:65], v[64:65], 1.0 op_sel_hi:[1,0]
	v_rcp_f32_e32 v70, v70
	v_rcp_f32_e32 v71, v71
	v_rcp_f32_e32 v72, v72
	v_rcp_f32_e32 v73, v73
	v_rcp_f32_e32 v74, v74
	v_rcp_f32_e32 v75, v75
	v_rcp_f32_e32 v64, v64
	v_rcp_f32_e32 v65, v65
	s_nop 0
	v_add_u32_e32 v63, 0x80, v141
	v_mul_f32_e32 v62, v168, v168
	v_pk_mul_f32 v[54:55], v[54:55], v[66:67]
	v_pk_mul_f32 v[64:65], v[62:63], v[64:65] op_sel_hi:[0,1]
	v_pk_mul_f32 v[54:55], v[54:55], v[64:65]
	v_pk_mul_f32 v[52:53], v[52:53], v[60:61]
	v_pk_mul_f32 v[50:51], v[50:51], v[58:59]
	v_pk_mul_f32 v[58:59], v[62:63], v[70:71] op_sel_hi:[0,1]
	v_pk_mul_f32 v[60:61], v[62:63], v[74:75] op_sel_hi:[0,1]
	v_pk_mul_f32 v[56:57], v[56:57], v[68:69]
	v_pk_mul_f32 v[66:67], v[62:63], v[72:73] op_sel_hi:[0,1]
	v_pk_mul_f32 v[60:61], v[52:53], v[60:61]
	v_pk_mul_f32 v[52:53], v[50:51], v[58:59]
	v_cvt_pk_bf16_f32 v50, v54, v55
	v_mad_i64_i32 v[54:55], s[12:13], v63, s91, v[114:115]
	v_pk_mul_f32 v[56:57], v[56:57], v[66:67]
	v_lshl_add_u64 v[54:55], v[54:55], 0, v[116:117]
	v_cvt_pk_bf16_f32 v51, v56, v57
	v_cvt_pk_bf16_f32 v52, v52, v53
	v_cvt_pk_bf16_f32 v53, v60, v61
	s_cmp_eq_u32 s98, 1
	s_cbranch_scc1 .Lwt_12
	global_store_dwordx4 v[54:55], v[50:53], off
	s_branch .Lwtd_12

.Lwtd_12:
	s_nop 1
	v_mul_f32_e32 v52, 0xbfb8aa3b, v169
	v_pk_mul_f32 v[54:55], v[34:35], v[52:53] op_sel_hi:[1,0]
	v_pk_mul_f32 v[56:57], v[40:41], v[52:53] op_sel_hi:[1,0]
	v_pk_mul_f32 v[58:59], v[36:37], v[52:53] op_sel_hi:[1,0]
	v_pk_mul_f32 v[52:53], v[38:39], v[52:53] op_sel_hi:[1,0]
	v_exp_f32_e32 v54, v54
	v_exp_f32_e32 v55, v55
	v_exp_f32_e32 v56, v56
	v_exp_f32_e32 v57, v57
	v_exp_f32_e32 v58, v58
	v_exp_f32_e32 v59, v59
	v_exp_f32_e32 v52, v52
	v_exp_f32_e32 v53, v53
	v_pk_add_f32 v[54:55], v[54:55], 1.0 op_sel_hi:[1,0]
	v_pk_add_f32 v[56:57], v[56:57], 1.0 op_sel_hi:[1,0]
	v_pk_add_f32 v[58:59], v[58:59], 1.0 op_sel_hi:[1,0]
	v_pk_add_f32 v[52:53], v[52:53], 1.0 op_sel_hi:[1,0]
	v_rcp_f32_e32 v54, v54
	v_rcp_f32_e32 v55, v55
	v_rcp_f32_e32 v56, v56
	v_rcp_f32_e32 v57, v57
	v_rcp_f32_e32 v58, v58
	v_rcp_f32_e32 v59, v59
	v_rcp_f32_e32 v52, v52
	v_rcp_f32_e32 v53, v53
	s_nop 0
	v_add_u32_e32 v51, 0x90, v141
	v_mul_f32_e32 v50, v169, v169
	v_pk_mul_f32 v[38:39], v[38:39], v[46:47]
	v_pk_mul_f32 v[46:47], v[50:51], v[52:53] op_sel_hi:[0,1]
	v_pk_mul_f32 v[38:39], v[38:39], v[46:47]
	v_pk_mul_f32 v[36:37], v[36:37], v[44:45]
	v_pk_mul_f32 v[34:35], v[34:35], v[42:43]
	v_pk_mul_f32 v[42:43], v[50:51], v[54:55] op_sel_hi:[0,1]
	v_pk_mul_f32 v[44:45], v[50:51], v[58:59] op_sel_hi:[0,1]
	v_pk_mul_f32 v[40:41], v[40:41], v[48:49]
	v_pk_mul_f32 v[48:49], v[50:51], v[56:57] op_sel_hi:[0,1]
	v_pk_mul_f32 v[44:45], v[36:37], v[44:45]
	v_pk_mul_f32 v[36:37], v[34:35], v[42:43]
	v_cvt_pk_bf16_f32 v34, v38, v39
	v_mad_i64_i32 v[38:39], s[12:13], v51, s91, v[114:115]
	v_pk_mul_f32 v[40:41], v[40:41], v[48:49]
	v_lshl_add_u64 v[38:39], v[38:39], 0, v[116:117]
	v_cvt_pk_bf16_f32 v35, v40, v41
	v_cvt_pk_bf16_f32 v36, v36, v37
	v_cvt_pk_bf16_f32 v37, v44, v45
	s_cmp_eq_u32 s98, 1
	s_cbranch_scc1 .Lwt_13
	global_store_dwordx4 v[38:39], v[34:37], off
	s_branch .Lwtd_13

.Lwtd_13:
	s_nop 1
	v_mul_f32_e32 v36, 0xbfb8aa3b, v149
	v_pk_mul_f32 v[38:39], v[18:19], v[36:37] op_sel_hi:[1,0]
	v_pk_mul_f32 v[40:41], v[24:25], v[36:37] op_sel_hi:[1,0]
	v_pk_mul_f32 v[42:43], v[20:21], v[36:37] op_sel_hi:[1,0]
	v_pk_mul_f32 v[36:37], v[22:23], v[36:37] op_sel_hi:[1,0]
	v_exp_f32_e32 v38, v38
	v_exp_f32_e32 v39, v39
	v_exp_f32_e32 v40, v40
	v_exp_f32_e32 v41, v41
	v_exp_f32_e32 v42, v42
	v_exp_f32_e32 v43, v43
	v_exp_f32_e32 v36, v36
	v_exp_f32_e32 v37, v37
	v_pk_add_f32 v[38:39], v[38:39], 1.0 op_sel_hi:[1,0]
	v_pk_add_f32 v[40:41], v[40:41], 1.0 op_sel_hi:[1,0]
	v_pk_add_f32 v[42:43], v[42:43], 1.0 op_sel_hi:[1,0]
	v_pk_add_f32 v[36:37], v[36:37], 1.0 op_sel_hi:[1,0]
	v_rcp_f32_e32 v38, v38
	v_rcp_f32_e32 v39, v39
	v_rcp_f32_e32 v40, v40
	v_rcp_f32_e32 v41, v41
	v_rcp_f32_e32 v42, v42
	v_rcp_f32_e32 v43, v43
	v_rcp_f32_e32 v36, v36
	v_rcp_f32_e32 v37, v37
	s_nop 0
	v_add_u32_e32 v35, 0xa0, v141
	v_mul_f32_e32 v34, v149, v149
	v_pk_mul_f32 v[22:23], v[22:23], v[30:31]
	v_pk_mul_f32 v[30:31], v[34:35], v[36:37] op_sel_hi:[0,1]
	v_pk_mul_f32 v[22:23], v[22:23], v[30:31]
	v_pk_mul_f32 v[20:21], v[20:21], v[28:29]
	v_pk_mul_f32 v[18:19], v[18:19], v[26:27]
	v_pk_mul_f32 v[26:27], v[34:35], v[38:39] op_sel_hi:[0,1]
	v_pk_mul_f32 v[28:29], v[34:35], v[42:43] op_sel_hi:[0,1]
	v_pk_mul_f32 v[24:25], v[24:25], v[32:33]
	v_pk_mul_f32 v[32:33], v[34:35], v[40:41] op_sel_hi:[0,1]
	v_pk_mul_f32 v[28:29], v[20:21], v[28:29]
	v_pk_mul_f32 v[20:21], v[18:19], v[26:27]
	v_cvt_pk_bf16_f32 v18, v22, v23
	v_mad_i64_i32 v[22:23], s[12:13], v35, s91, v[114:115]
	v_pk_mul_f32 v[24:25], v[24:25], v[32:33]
	v_lshl_add_u64 v[22:23], v[22:23], 0, v[116:117]
	v_cvt_pk_bf16_f32 v19, v24, v25
	v_cvt_pk_bf16_f32 v20, v20, v21
	v_cvt_pk_bf16_f32 v21, v28, v29
	s_cmp_eq_u32 s98, 1
	s_cbranch_scc1 .Lwt_14
	global_store_dwordx4 v[22:23], v[18:21], off
	s_branch .Lwtd_14

.Lwtd_14:
	s_nop 1
	v_add_u32_e32 v19, 0xb0, v141
	v_mul_f32_e32 v18, v140, v140
	v_mul_f32_e32 v20, 0xbfb8aa3b, v140
	v_pk_mul_f32 v[22:23], v[2:3], v[20:21] op_sel_hi:[1,0]
	v_pk_mul_f32 v[24:25], v[8:9], v[20:21] op_sel_hi:[1,0]
	v_pk_mul_f32 v[26:27], v[4:5], v[20:21] op_sel_hi:[1,0]
	v_pk_mul_f32 v[20:21], v[6:7], v[20:21] op_sel_hi:[1,0]
	v_exp_f32_e32 v22, v22
	v_exp_f32_e32 v23, v23
	v_exp_f32_e32 v24, v24
	v_exp_f32_e32 v25, v25
	v_exp_f32_e32 v26, v26
	v_exp_f32_e32 v27, v27
	v_exp_f32_e32 v20, v20
	v_exp_f32_e32 v21, v21
	v_pk_add_f32 v[22:23], v[22:23], 1.0 op_sel_hi:[1,0]
	v_pk_add_f32 v[24:25], v[24:25], 1.0 op_sel_hi:[1,0]
	v_pk_add_f32 v[26:27], v[26:27], 1.0 op_sel_hi:[1,0]
	v_pk_add_f32 v[20:21], v[20:21], 1.0 op_sel_hi:[1,0]
	v_rcp_f32_e32 v22, v22
	v_rcp_f32_e32 v23, v23
	v_rcp_f32_e32 v24, v24
	v_rcp_f32_e32 v25, v25
	v_rcp_f32_e32 v26, v26
	v_rcp_f32_e32 v27, v27
	v_rcp_f32_e32 v20, v20
	v_rcp_f32_e32 v21, v21
	s_nop 0
	v_pk_mul_f32 v[6:7], v[6:7], v[14:15]
	v_pk_mul_f32 v[14:15], v[18:19], v[20:21] op_sel_hi:[0,1]
	v_pk_mul_f32 v[6:7], v[6:7], v[14:15]
	v_pk_mul_f32 v[4:5], v[4:5], v[12:13]
	v_pk_mul_f32 v[2:3], v[2:3], v[10:11]
	v_pk_mul_f32 v[10:11], v[18:19], v[22:23] op_sel_hi:[0,1]
	v_pk_mul_f32 v[12:13], v[18:19], v[26:27] op_sel_hi:[0,1]
	v_pk_mul_f32 v[12:13], v[4:5], v[12:13]
	v_pk_mul_f32 v[4:5], v[2:3], v[10:11]
	v_cvt_pk_bf16_f32 v2, v6, v7
	v_mad_i64_i32 v[6:7], s[12:13], v19, s91, v[114:115]
	v_pk_mul_f32 v[8:9], v[8:9], v[16:17]
	v_pk_mul_f32 v[16:17], v[18:19], v[24:25] op_sel_hi:[0,1]
	v_lshl_add_u64 v[6:7], v[6:7], 0, v[116:117]
	v_pk_mul_f32 v[8:9], v[8:9], v[16:17]
	s_nop 0
	v_cvt_pk_bf16_f32 v3, v8, v9
	v_cvt_pk_bf16_f32 v4, v4, v5
	v_cvt_pk_bf16_f32 v5, v12, v13
	s_cmp_eq_u32 s98, 1
	s_cbranch_scc1 .Lwt_15
	global_store_dwordx4 v[6:7], v[2:5], off
	s_branch .Lwtd_15
